# attention: the slc/window gate-logit loads issued together with the cmp one (held in two free VGPRs) instead of after each branch; + compress, EpiResid, PV edits
# baseline (speedup 1.0000x reference)
; DI unsigned pk2(float lo, float hi) { f32x2 v = {lo, hi}; bf16x2n b = __builtin_convertvector(v, bf16x2n); return __builtin_bit_cast(unsigned, b); }
; DI float sigmoid_f(float x) { return fast_rcp(1.f + fast_exp2(-1.44269504f * x)); }
; #define ATT_GL(k) bf2f(Vt[(unsigned)(VR_GL + head * 3 + (k)) * (unsigned)M + m])
; DI void unit(const int wv, const Params& p, int l, int b, int g, int qt, LAS unsigned char* lds) {
;     ...
;         const float lt = lr + __shfl_xor(lr, 32); const float gt = sigmoid_f(ATT_GL(2)) * ((lt > 0.f) ? 1.f / lt : 0.f);
; #pragma unroll
;         for (int dt = 0; dt < 4; ++dt)
; #pragma unroll
;             for (int i = 0; i < 8; ++i) { const unsigned pv = outp[(dt * 8 + i) * 64]; outp[(dt * 8 + i) * 64] = pk2(bflo(pv) + gt * O[dt][2 * i], bfhi(pv) + gt * O[dt][2 * i + 1]); }
;     }
;     bf16_t* op = (bf16_t*)(p.ws + WS_CONCAT) + (size_t)(m * (unsigned)D + 1024 + head * 128 + 4 * h);
; #pragma unroll
;     for (int dt = 0; dt < 4; ++dt)
; #pragma unroll
;         for (int gq = 0; gq < 4; ++gq) { u32x2 w; w.x = outp[(dt * 8 + 2 * gq) * 64]; w.y = outp[(dt * 8 + 2 * gq + 1) * 64];
;             *(u32x2*)(op + 32 * dt + 8 * gq) = w; }
.LBB0_504:
	s_mov_b32 s0, 0x808000
	v_add3_u32 v160, v222, v212, s0
	v_lshl_add_u64 v[64:65], v[160:161], 1, s[82:83]
	s_barrier
	v_mov_b32_e32 v64, v208
	ds_bpermute_b32 v65, v214, v197
	ds_read_b32 v67, v221
	v_readlane_b32 s85, v254, 50
	v_readlane_b32 s4, v254, 34
	s_waitcnt lgkmcnt(1)
	v_add_f32_e32 v65, v197, v65
	v_div_scale_f32 v68, s[0:1], v65, v65, 1.0
	v_rcp_f32_e32 v69, v68
	v_div_scale_f32 v70, vcc, 1.0, v65, 1.0
	s_waitcnt lgkmcnt(0)
	v_lshlrev_b32_e32 v66, 16, v67
	v_fma_f32 v71, -v68, v69, 1.0
	v_fmac_f32_e32 v69, v71, v69
	v_mul_f32_e32 v71, v70, v69
	v_fma_f32 v72, -v68, v71, v70
	v_fmac_f32_e32 v71, v72, v69
	v_fma_f32 v68, -v68, v71, v70
	v_div_fmas_f32 v68, v68, v69, v71
	v_div_fixup_f32 v68, v68, v65, 1.0
	v_cmp_lt_f32_e32 vcc, 0, v65
	v_and_b32_e32 v67, 0xffff0000, v67
	s_movk_i32 s0, 0x400
	v_cndmask_b32_e32 v65, 0, v68, vcc
	s_waitcnt vmcnt(0)
	v_lshlrev_b32_e32 v64, 16, v64
	v_mul_f32_e32 v64, 0xbfb8aa3b, v64
	v_exp_f32_e32 v64, v64
	s_nop 0
	v_add_f32_e32 v64, 1.0, v64
	v_rcp_f32_e32 v64, v64
	s_nop 0
	v_mul_f32_e32 v64, v65, v64
	v_pk_fma_f32 v[48:49], v[48:49], v[64:65], v[66:67] op_sel_hi:[1,0,1]
	s_nop 0
	v_cvt_pk_bf16_f32 v48, v48, v49
	ds_write_b32 v221, v48
	ds_read2st64_b32 v[48:49], v221 offset1:1
	s_waitcnt lgkmcnt(0)
	v_lshlrev_b32_e32 v66, 16, v49
	v_and_b32_e32 v67, 0xffff0000, v49
	v_pk_fma_f32 v[50:51], v[50:51], v[64:65], v[66:67] op_sel_hi:[1,0,1]
	s_nop 0
	v_cvt_pk_bf16_f32 v49, v50, v51
	ds_write_b32 v221, v49 offset:256
	ds_read2st64_b32 v[50:51], v221 offset0:1 offset1:2
	s_waitcnt lgkmcnt(0)
	v_lshlrev_b32_e32 v66, 16, v51
	v_and_b32_e32 v67, 0xffff0000, v51
	v_pk_fma_f32 v[52:53], v[52:53], v[64:65], v[66:67] op_sel_hi:[1,0,1]
	s_nop 0
	v_cvt_pk_bf16_f32 v49, v52, v53
	ds_write_b32 v221, v49 offset:512
	ds_read2st64_b32 v[52:53], v221 offset0:2 offset1:3
	s_waitcnt lgkmcnt(0)
	v_lshlrev_b32_e32 v66, 16, v53
	v_and_b32_e32 v67, 0xffff0000, v53
	v_pk_fma_f32 v[54:55], v[54:55], v[64:65], v[66:67] op_sel_hi:[1,0,1]
	s_nop 0
	v_cvt_pk_bf16_f32 v49, v54, v55
	ds_write_b32 v221, v49 offset:768
	ds_read2st64_b32 v[54:55], v221 offset0:3 offset1:4
	s_waitcnt lgkmcnt(0)
	v_lshlrev_b32_e32 v66, 16, v55
	v_and_b32_e32 v67, 0xffff0000, v55
	v_pk_fma_f32 v[56:57], v[56:57], v[64:65], v[66:67] op_sel_hi:[1,0,1]
	v_mov_b32_e32 v53, v54
	v_cvt_pk_bf16_f32 v49, v56, v57
	ds_write_b32 v221, v49 offset:1024
	ds_read2st64_b32 v[56:57], v221 offset0:4 offset1:5
	s_waitcnt lgkmcnt(0)
	v_lshlrev_b32_e32 v66, 16, v57
	v_and_b32_e32 v67, 0xffff0000, v57
	v_pk_fma_f32 v[58:59], v[58:59], v[64:65], v[66:67] op_sel_hi:[1,0,1]
	s_nop 0
	v_cvt_pk_bf16_f32 v49, v58, v59
	ds_write_b32 v221, v49 offset:1280
	ds_read2st64_b32 v[58:59], v221 offset0:5 offset1:6
	s_waitcnt lgkmcnt(0)
	v_lshlrev_b32_e32 v66, 16, v59
	v_and_b32_e32 v67, 0xffff0000, v59
	v_pk_fma_f32 v[60:61], v[60:61], v[64:65], v[66:67] op_sel_hi:[1,0,1]
	v_mov_b32_e32 v57, v58
	v_cvt_pk_bf16_f32 v49, v60, v61
	ds_write_b32 v221, v49 offset:1536
	ds_read2st64_b32 v[60:61], v221 offset0:6 offset1:7
	s_waitcnt lgkmcnt(0)
	v_lshlrev_b32_e32 v66, 16, v61
	v_and_b32_e32 v67, 0xffff0000, v61
	v_pk_fma_f32 v[62:63], v[62:63], v[64:65], v[66:67] op_sel_hi:[1,0,1]
	s_nop 0
	v_cvt_pk_bf16_f32 v49, v62, v63
	ds_write_b32 v221, v49 offset:1792
	ds_read2st64_b32 v[62:63], v221 offset0:7 offset1:8
	v_mov_b32_e32 v49, v50
	s_waitcnt lgkmcnt(0)
	v_lshlrev_b32_e32 v66, 16, v63
	v_and_b32_e32 v67, 0xffff0000, v63
	v_pk_fma_f32 v[32:33], v[32:33], v[64:65], v[66:67] op_sel_hi:[1,0,1]
	v_mov_b32_e32 v61, v62
	v_cvt_pk_bf16_f32 v32, v32, v33
	ds_write_b32 v221, v32 offset:2048
	ds_read2st64_b32 v[32:33], v221 offset0:8 offset1:9
	s_waitcnt lgkmcnt(0)
	v_lshlrev_b32_e32 v66, 16, v33
	v_and_b32_e32 v67, 0xffff0000, v33
	v_pk_fma_f32 v[34:35], v[34:35], v[64:65], v[66:67] op_sel_hi:[1,0,1]
	s_nop 0
	v_cvt_pk_bf16_f32 v33, v34, v35
	ds_write_b32 v221, v33 offset:2304
	ds_read2st64_b32 v[34:35], v221 offset0:9 offset1:10
	s_waitcnt lgkmcnt(0)
	v_lshlrev_b32_e32 v66, 16, v35
	v_and_b32_e32 v67, 0xffff0000, v35
	v_pk_fma_f32 v[36:37], v[36:37], v[64:65], v[66:67] op_sel_hi:[1,0,1]
	s_nop 0
	v_cvt_pk_bf16_f32 v33, v36, v37
	ds_write_b32 v221, v33 offset:2560
	ds_read2st64_b32 v[36:37], v221 offset0:10 offset1:11
	s_waitcnt lgkmcnt(0)
	v_lshlrev_b32_e32 v66, 16, v37
	v_and_b32_e32 v67, 0xffff0000, v37
	v_pk_fma_f32 v[38:39], v[38:39], v[64:65], v[66:67] op_sel_hi:[1,0,1]
	s_nop 0
	v_cvt_pk_bf16_f32 v33, v38, v39
	ds_write_b32 v221, v33 offset:2816
	ds_read2st64_b32 v[38:39], v221 offset0:11 offset1:12
	s_waitcnt lgkmcnt(0)
	v_lshlrev_b32_e32 v66, 16, v39
	v_and_b32_e32 v67, 0xffff0000, v39
	v_pk_fma_f32 v[40:41], v[40:41], v[64:65], v[66:67] op_sel_hi:[1,0,1]
	v_mov_b32_e32 v37, v38
	v_cvt_pk_bf16_f32 v33, v40, v41
	ds_write_b32 v221, v33 offset:3072
	ds_read2st64_b32 v[40:41], v221 offset0:12 offset1:13
	s_waitcnt lgkmcnt(0)
	v_lshlrev_b32_e32 v66, 16, v41
	v_and_b32_e32 v67, 0xffff0000, v41
	v_pk_fma_f32 v[42:43], v[42:43], v[64:65], v[66:67] op_sel_hi:[1,0,1]
	s_nop 0
	v_cvt_pk_bf16_f32 v33, v42, v43
	ds_write_b32 v221, v33 offset:3328
	ds_read2st64_b32 v[42:43], v221 offset0:13 offset1:14
	s_waitcnt lgkmcnt(0)
	v_lshlrev_b32_e32 v66, 16, v43
	v_and_b32_e32 v67, 0xffff0000, v43
	v_pk_fma_f32 v[44:45], v[44:45], v[64:65], v[66:67] op_sel_hi:[1,0,1]
	v_mov_b32_e32 v41, v42
	v_cvt_pk_bf16_f32 v33, v44, v45
	ds_write_b32 v221, v33 offset:3584
	ds_read2st64_b32 v[44:45], v221 offset0:14 offset1:15
	s_waitcnt lgkmcnt(0)
	v_lshlrev_b32_e32 v66, 16, v45
	v_and_b32_e32 v67, 0xffff0000, v45
	v_pk_fma_f32 v[46:47], v[46:47], v[64:65], v[66:67] op_sel_hi:[1,0,1]
	s_nop 0
	v_cvt_pk_bf16_f32 v33, v46, v47
	ds_write_b32 v221, v33 offset:3840
	ds_read2st64_b32 v[46:47], v221 offset0:15 offset1:16
	v_mov_b32_e32 v33, v34
	s_waitcnt lgkmcnt(0)
; DI unsigned pk2(float lo, float hi) { f32x2 v = {lo, hi}; bf16x2n b = __builtin_convertvector(v, bf16x2n); return __builtin_bit_cast(unsigned, b); }
; DI void unit(const int wv, const Params& p, int l, int b, int g, int qt, LAS unsigned char* lds) {
;     ...
;             for (int i = 0; i < 8; ++i) { const unsigned pv = outp[(dt * 8 + i) * 64]; outp[(dt * 8 + i) * 64] = pk2(bflo(pv) + gt * O[dt][2 * i], bfhi(pv) + gt * O[dt][2 * i + 1]); }
;     }
;     bf16_t* op = (bf16_t*)(p.ws + WS_CONCAT) + (size_t)(m * (unsigned)D + 1024 + head * 128 + 4 * h);
; #pragma unroll
;     for (int dt = 0; dt < 4; ++dt)
; #pragma unroll
;         for (int gq = 0; gq < 4; ++gq) { u32x2 w; w.x = outp[(dt * 8 + 2 * gq) * 64]; w.y = outp[(dt * 8 + 2 * gq + 1) * 64];
;             *(u32x2*)(op + 32 * dt + 8 * gq) = w; }
	v_lshlrev_b32_e32 v66, 16, v47
	v_and_b32_e32 v67, 0xffff0000, v47
	v_pk_fma_f32 v[16:17], v[16:17], v[64:65], v[66:67] op_sel_hi:[1,0,1]
	v_mov_b32_e32 v45, v46
	v_cvt_pk_bf16_f32 v16, v16, v17
	ds_write_b32 v221, v16 offset:4096
	ds_read2st64_b32 v[16:17], v221 offset0:16 offset1:17
	s_waitcnt lgkmcnt(0)
	v_lshlrev_b32_e32 v66, 16, v17
	v_and_b32_e32 v67, 0xffff0000, v17
	v_pk_fma_f32 v[18:19], v[18:19], v[64:65], v[66:67] op_sel_hi:[1,0,1]
	s_nop 0
	v_cvt_pk_bf16_f32 v17, v18, v19
	ds_write_b32 v221, v17 offset:4352
	ds_read2st64_b32 v[18:19], v221 offset0:17 offset1:18
	s_waitcnt lgkmcnt(0)
	v_lshlrev_b32_e32 v66, 16, v19
	v_and_b32_e32 v67, 0xffff0000, v19
	v_pk_fma_f32 v[20:21], v[20:21], v[64:65], v[66:67] op_sel_hi:[1,0,1]
	s_nop 0
	v_cvt_pk_bf16_f32 v17, v20, v21
	ds_write_b32 v221, v17 offset:4608
	ds_read2st64_b32 v[20:21], v221 offset0:18 offset1:19
	s_waitcnt lgkmcnt(0)
	v_lshlrev_b32_e32 v66, 16, v21
	v_and_b32_e32 v67, 0xffff0000, v21
	v_pk_fma_f32 v[22:23], v[22:23], v[64:65], v[66:67] op_sel_hi:[1,0,1]
	s_nop 0
	v_cvt_pk_bf16_f32 v17, v22, v23
	ds_write_b32 v221, v17 offset:4864
	ds_read2st64_b32 v[22:23], v221 offset0:19 offset1:20
	s_waitcnt lgkmcnt(0)
	v_lshlrev_b32_e32 v66, 16, v23
	v_and_b32_e32 v67, 0xffff0000, v23
	v_pk_fma_f32 v[24:25], v[24:25], v[64:65], v[66:67] op_sel_hi:[1,0,1]
	v_mov_b32_e32 v21, v22
	v_cvt_pk_bf16_f32 v17, v24, v25
	ds_write_b32 v221, v17 offset:5120
	ds_read2st64_b32 v[24:25], v221 offset0:20 offset1:21
	s_waitcnt lgkmcnt(0)
	v_lshlrev_b32_e32 v66, 16, v25
	v_and_b32_e32 v67, 0xffff0000, v25
	v_pk_fma_f32 v[26:27], v[26:27], v[64:65], v[66:67] op_sel_hi:[1,0,1]
	s_nop 0
	v_cvt_pk_bf16_f32 v17, v26, v27
	ds_write_b32 v221, v17 offset:5376
	ds_read2st64_b32 v[26:27], v221 offset0:21 offset1:22
	s_waitcnt lgkmcnt(0)
	v_lshlrev_b32_e32 v66, 16, v27
	v_and_b32_e32 v67, 0xffff0000, v27
	v_pk_fma_f32 v[28:29], v[28:29], v[64:65], v[66:67] op_sel_hi:[1,0,1]
	v_mov_b32_e32 v25, v26
	v_cvt_pk_bf16_f32 v17, v28, v29
	ds_write_b32 v221, v17 offset:5632
	ds_read2st64_b32 v[28:29], v221 offset0:22 offset1:23
	v_lshlrev_b32_e32 v17, 2, v211
	v_lshl_or_b32 v17, v212, 11, v17
	v_or3_b32 v160, v17, v210, s0
	v_readlane_b32 s0, v254, 11
	s_waitcnt lgkmcnt(0)
	v_lshlrev_b32_e32 v66, 16, v29
	v_and_b32_e32 v67, 0xffff0000, v29
	v_pk_fma_f32 v[30:31], v[30:31], v[64:65], v[66:67] op_sel_hi:[1,0,1]
	v_readlane_b32 s1, v254, 12
	v_cvt_pk_bf16_f32 v19, v30, v31
	ds_write_b32 v221, v19 offset:5888
	ds_read2st64_b32 v[30:31], v221 offset0:23 offset1:24
	v_lshl_add_u64 v[66:67], v[160:161], 1, s[0:1]
	global_store_dwordx2 v[66:67], v[48:49], off
	global_store_dwordx2 v[66:67], v[32:33], off offset:64
	v_mov_b32_e32 v17, v18
	s_waitcnt lgkmcnt(0)
	v_lshlrev_b32_e32 v48, 16, v31
	v_and_b32_e32 v49, 0xffff0000, v31
	v_pk_fma_f32 v[0:1], v[0:1], v[64:65], v[48:49] op_sel_hi:[1,0,1]
	global_store_dwordx2 v[66:67], v[16:17], off offset:128
	v_cvt_pk_bf16_f32 v0, v0, v1
	ds_write_b32 v221, v0 offset:6144
	ds_read2st64_b32 v[0:1], v221 offset0:24 offset1:25
	v_mov_b32_e32 v29, v30
	global_store_dwordx2 v[66:67], v[52:53], off offset:16
	global_store_dwordx2 v[66:67], v[56:57], off offset:32
	global_store_dwordx2 v[66:67], v[60:61], off offset:48
	s_waitcnt lgkmcnt(0)
	v_lshlrev_b32_e32 v48, 16, v1
	v_and_b32_e32 v49, 0xffff0000, v1
	v_pk_fma_f32 v[2:3], v[2:3], v[64:65], v[48:49] op_sel_hi:[1,0,1]
	global_store_dwordx2 v[66:67], v[36:37], off offset:80
	v_cvt_pk_bf16_f32 v1, v2, v3
	ds_write_b32 v221, v1 offset:6400
	ds_read2st64_b32 v[2:3], v221 offset0:25 offset1:26
	global_store_dwordx2 v[66:67], v[40:41], off offset:96
	global_store_dwordx2 v[66:67], v[44:45], off offset:112
	global_store_dwordx2 v[66:67], v[20:21], off offset:144
	global_store_dwordx2 v[66:67], v[24:25], off offset:160
	s_waitcnt lgkmcnt(0)
	v_lshlrev_b32_e32 v32, 16, v3
	v_and_b32_e32 v33, 0xffff0000, v3
	v_pk_fma_f32 v[4:5], v[4:5], v[64:65], v[32:33] op_sel_hi:[1,0,1]
	global_store_dwordx2 v[66:67], v[28:29], off offset:176
	v_cvt_pk_bf16_f32 v1, v4, v5
	ds_write_b32 v221, v1 offset:6656
	ds_read2st64_b32 v[4:5], v221 offset0:26 offset1:27
	s_waitcnt lgkmcnt(0)
	v_lshlrev_b32_e32 v32, 16, v5
	v_and_b32_e32 v33, 0xffff0000, v5
	v_pk_fma_f32 v[6:7], v[6:7], v[64:65], v[32:33] op_sel_hi:[1,0,1]
	s_nop 0
	v_cvt_pk_bf16_f32 v1, v6, v7
	ds_write_b32 v221, v1 offset:6912
	ds_read2st64_b32 v[6:7], v221 offset0:27 offset1:28
	s_waitcnt lgkmcnt(0)
	v_lshlrev_b32_e32 v16, 16, v7
	v_and_b32_e32 v17, 0xffff0000, v7
	v_pk_fma_f32 v[8:9], v[8:9], v[64:65], v[16:17] op_sel_hi:[1,0,1]
	v_mov_b32_e32 v5, v6
	v_cvt_pk_bf16_f32 v1, v8, v9
	ds_write_b32 v221, v1 offset:7168
	ds_read2st64_b32 v[8:9], v221 offset0:28 offset1:29
	global_store_dwordx2 v[66:67], v[4:5], off offset:208
	s_waitcnt lgkmcnt(0)
	v_lshlrev_b32_e32 v16, 16, v9
	v_and_b32_e32 v17, 0xffff0000, v9
	v_pk_fma_f32 v[10:11], v[10:11], v[64:65], v[16:17] op_sel_hi:[1,0,1]
	s_nop 0
	v_cvt_pk_bf16_f32 v1, v10, v11
	ds_write_b32 v221, v1 offset:7424
	ds_read2st64_b32 v[10:11], v221 offset0:29 offset1:30
	v_mov_b32_e32 v1, v2
	global_store_dwordx2 v[66:67], v[0:1], off offset:192
	s_waitcnt lgkmcnt(0)
	v_lshlrev_b32_e32 v0, 16, v11
	v_and_b32_e32 v1, 0xffff0000, v11
	v_pk_fma_f32 v[0:1], v[12:13], v[64:65], v[0:1] op_sel_hi:[1,0,1]
	v_mov_b32_e32 v9, v10
	v_cvt_pk_bf16_f32 v0, v0, v1
	ds_write_b32 v221, v0 offset:7680
	ds_read2st64_b32 v[0:1], v221 offset0:30 offset1:31
	global_store_dwordx2 v[66:67], v[8:9], off offset:224
	s_waitcnt lgkmcnt(0)
	v_lshlrev_b32_e32 v2, 16, v1
	v_and_b32_e32 v3, 0xffff0000, v1
	v_pk_fma_f32 v[2:3], v[14:15], v[64:65], v[2:3] op_sel_hi:[1,0,1]
	s_nop 0
	v_cvt_pk_bf16_f32 v1, v2, v3
	ds_write_b32 v221, v1 offset:7936
	global_store_dwordx2 v[66:67], v[0:1], off offset:240

; DI unsigned pk2(float lo, float hi) { f32x2 v = {lo, hi}; bf16x2n b = __builtin_convertvector(v, bf16x2n); return __builtin_bit_cast(unsigned, b); }
; DI float sigmoid_f(float x) { return fast_rcp(1.f + fast_exp2(-1.44269504f * x)); }
; #define ATT_GL(k) bf2f(Vt[(unsigned)(VR_GL + head * 3 + (k)) * (unsigned)M + m])
; DI void unit(const int wv, const Params& p, int l, int b, int g, int qt, LAS unsigned char* lds) {
;     ...
;     { const float gt = sigmoid_f(ATT_GL(0));
; #pragma unroll
;       for (int dt = 0; dt < 4; ++dt)
; #pragma unroll
;           for (int i = 0; i < 8; ++i) outp[(dt * 8 + i) * 64] = pk2(gt * O[dt][2 * i], gt * O[dt][2 * i + 1]); }
;     __syncthreads();
;     unsigned long long wuni = 0ull, wall = ~0ull;
;     {
;         for (int t8 = 0; t8 < 8; ++t8) {
;             const float v = imp[(8 * wave + t8) * 64 + lane];
;             const bool valid = lane <= qt, forced = (lane == 0) || (lane == qt) || (lane == qt - 1);
;             const float sc = valid ? (v + (forced ? 1000.f : 0.f)) : -1e30f;
.LBB0_544:
	v_mul_u32_u24_e32 v222, 0xc000, v194
	s_mov_b32 s0, 0x800000
	v_add3_u32 v160, v212, v222, s0
	v_lshl_add_u64 v[64:65], v[160:161], 1, s[82:83]
	s_barrier
	s_mov_b64 s[98:99], 0x8000
	v_lshl_add_u64 v[250:251], v[64:65], 0, s[98:99]
	global_load_ushort v207, v[250:251], off
	v_lshl_add_u64 v[250:251], v[250:251], 0, s[98:99]
	global_load_ushort v208, v[250:251], off
	global_load_ushort v64, v[64:65], off
	v_lshlrev_b32_e32 v65, 13, v191
	v_lshlrev_b32_e32 v66, 2, v193
	v_readlane_b32 s0, v254, 36
	v_cmp_eq_u32_e32 vcc, 0, v193
	s_add_i32 s22, s85, 1
	v_add3_u32 v221, s0, v65, v66
	v_readlane_b32 s0, v254, 35
	s_mov_b32 s6, 0
	s_waitcnt vmcnt(0)
	v_lshlrev_b32_e32 v64, 16, v64
	v_mul_f32_e32 v64, 0xbfb8aa3b, v64
	v_exp_f32_e32 v64, v64
	s_nop 0
	v_add_f32_e32 v64, 1.0, v64
	v_rcp_f32_e32 v64, v64
	s_nop 0
	v_pk_mul_f32 v[48:49], v[48:49], v[64:65] op_sel_hi:[1,0]
	v_pk_mul_f32 v[50:51], v[50:51], v[64:65] op_sel_hi:[1,0]
	v_pk_mul_f32 v[0:1], v[0:1], v[64:65] op_sel_hi:[1,0]
	v_pk_mul_f32 v[52:53], v[52:53], v[64:65] op_sel_hi:[1,0]
	v_pk_mul_f32 v[54:55], v[54:55], v[64:65] op_sel_hi:[1,0]
	v_pk_mul_f32 v[56:57], v[56:57], v[64:65] op_sel_hi:[1,0]
	v_pk_mul_f32 v[58:59], v[58:59], v[64:65] op_sel_hi:[1,0]
	v_pk_mul_f32 v[60:61], v[60:61], v[64:65] op_sel_hi:[1,0]
	v_pk_mul_f32 v[62:63], v[62:63], v[64:65] op_sel_hi:[1,0]
	v_pk_mul_f32 v[32:33], v[32:33], v[64:65] op_sel_hi:[1,0]
	v_pk_mul_f32 v[34:35], v[34:35], v[64:65] op_sel_hi:[1,0]
	v_pk_mul_f32 v[36:37], v[36:37], v[64:65] op_sel_hi:[1,0]
	v_pk_mul_f32 v[38:39], v[38:39], v[64:65] op_sel_hi:[1,0]
	v_pk_mul_f32 v[40:41], v[40:41], v[64:65] op_sel_hi:[1,0]
	v_pk_mul_f32 v[42:43], v[42:43], v[64:65] op_sel_hi:[1,0]
	v_pk_mul_f32 v[44:45], v[44:45], v[64:65] op_sel_hi:[1,0]
	v_pk_mul_f32 v[46:47], v[46:47], v[64:65] op_sel_hi:[1,0]
	v_pk_mul_f32 v[16:17], v[16:17], v[64:65] op_sel_hi:[1,0]
	v_pk_mul_f32 v[18:19], v[18:19], v[64:65] op_sel_hi:[1,0]
	v_pk_mul_f32 v[20:21], v[20:21], v[64:65] op_sel_hi:[1,0]
	v_pk_mul_f32 v[22:23], v[22:23], v[64:65] op_sel_hi:[1,0]
	v_pk_mul_f32 v[24:25], v[24:25], v[64:65] op_sel_hi:[1,0]
	v_pk_mul_f32 v[26:27], v[26:27], v[64:65] op_sel_hi:[1,0]
	v_pk_mul_f32 v[28:29], v[28:29], v[64:65] op_sel_hi:[1,0]
	v_pk_mul_f32 v[30:31], v[30:31], v[64:65] op_sel_hi:[1,0]
	v_pk_mul_f32 v[2:3], v[2:3], v[64:65] op_sel_hi:[1,0]
	v_pk_mul_f32 v[4:5], v[4:5], v[64:65] op_sel_hi:[1,0]
	v_pk_mul_f32 v[6:7], v[6:7], v[64:65] op_sel_hi:[1,0]
	v_pk_mul_f32 v[8:9], v[8:9], v[64:65] op_sel_hi:[1,0]
	v_pk_mul_f32 v[10:11], v[10:11], v[64:65] op_sel_hi:[1,0]
	v_pk_mul_f32 v[12:13], v[12:13], v[64:65] op_sel_hi:[1,0]
	v_pk_mul_f32 v[14:15], v[14:15], v[64:65] op_sel_hi:[1,0]
	v_cvt_pk_bf16_f32 v48, v48, v49
	v_cvt_pk_bf16_f32 v49, v50, v51
	v_cvt_pk_bf16_f32 v0, v0, v1
	v_cvt_pk_bf16_f32 v50, v52, v53
	v_cvt_pk_bf16_f32 v51, v54, v55
	v_cvt_pk_bf16_f32 v52, v56, v57
	v_cvt_pk_bf16_f32 v53, v58, v59
	v_cvt_pk_bf16_f32 v54, v60, v61
	v_cvt_pk_bf16_f32 v55, v62, v63
	v_cvt_pk_bf16_f32 v32, v32, v33
	v_cvt_pk_bf16_f32 v33, v34, v35
	v_cvt_pk_bf16_f32 v34, v36, v37
	v_cvt_pk_bf16_f32 v35, v38, v39
	v_cvt_pk_bf16_f32 v36, v40, v41
	v_cvt_pk_bf16_f32 v37, v42, v43
	v_cvt_pk_bf16_f32 v38, v44, v45
	v_cvt_pk_bf16_f32 v39, v46, v47
	v_cvt_pk_bf16_f32 v16, v16, v17
	v_cvt_pk_bf16_f32 v17, v18, v19
	v_cvt_pk_bf16_f32 v18, v20, v21
	v_cvt_pk_bf16_f32 v19, v22, v23
	v_cvt_pk_bf16_f32 v20, v24, v25
	v_cvt_pk_bf16_f32 v21, v26, v27
	v_cvt_pk_bf16_f32 v22, v28, v29
	v_cvt_pk_bf16_f32 v23, v30, v31
	v_cvt_pk_bf16_f32 v1, v2, v3
	v_cvt_pk_bf16_f32 v2, v4, v5
	v_cvt_pk_bf16_f32 v3, v6, v7
	v_cvt_pk_bf16_f32 v4, v8, v9
	v_cvt_pk_bf16_f32 v5, v10, v11
	v_cvt_pk_bf16_f32 v6, v12, v13
	v_cvt_pk_bf16_f32 v7, v14, v15
	ds_write2st64_b32 v221, v48, v49 offset1:1
	ds_write2st64_b32 v221, v50, v51 offset0:2 offset1:3
	ds_write2st64_b32 v221, v52, v53 offset0:4 offset1:5
	ds_write2st64_b32 v221, v54, v55 offset0:6 offset1:7
	ds_write2st64_b32 v221, v32, v33 offset0:8 offset1:9
	ds_write2st64_b32 v221, v34, v35 offset0:10 offset1:11
	ds_write2st64_b32 v221, v36, v37 offset0:12 offset1:13
	ds_write2st64_b32 v221, v38, v39 offset0:14 offset1:15
	ds_write2st64_b32 v221, v16, v17 offset0:16 offset1:17
	ds_write2st64_b32 v221, v18, v19 offset0:18 offset1:19
	ds_write2st64_b32 v221, v20, v21 offset0:20 offset1:21
	ds_write2st64_b32 v221, v22, v23 offset0:22 offset1:23
	ds_write2st64_b32 v221, v0, v1 offset0:24 offset1:25
	ds_write2st64_b32 v221, v2, v3 offset0:26 offset1:27
	ds_write2st64_b32 v221, v4, v5 offset0:28 offset1:29
	ds_write2st64_b32 v221, v6, v7 offset0:30 offset1:31
	v_add_u32_e32 v0, s0, v66
	v_lshl_add_u32 v1, v191, 11, v0
	s_waitcnt lgkmcnt(0)
	s_barrier
	v_cmp_eq_u32_e64 s[0:1], s85, v193
	ds_read_b32 v3, v1
	s_or_b64 s[2:3], vcc, s[0:1]
	s_sub_i32 s0, 62, s76
	v_cmp_eq_u32_e64 s[0:1], s0, v193
	s_or_b64 s[0:1], s[2:3], s[0:1]
	v_mov_b32_e32 v1, 0x447a0000
	v_cndmask_b32_e64 v1, 0, v1, s[0:1]
	s_waitcnt lgkmcnt(0)
	v_add_f32_e32 v3, v1, v3
	v_cmp_ge_u32_e64 s[2:3], s85, v193
	v_mov_b32_e32 v2, 0
	s_nop 0
	v_cndmask_b32_e64 v3, v209, v3, s[2:3]
	v_sub_u32_e32 v238, 63, v193
	v_mov_b32_e32 v239, v3
	s_nop 0

; DI unsigned pk2(float lo, float hi) { f32x2 v = {lo, hi}; bf16x2n b = __builtin_convertvector(v, bf16x2n); return __builtin_bit_cast(unsigned, b); }
; DI float sigmoid_f(float x) { return fast_rcp(1.f + fast_exp2(-1.44269504f * x)); }
; #define ATT_GL(k) bf2f(Vt[(unsigned)(VR_GL + head * 3 + (k)) * (unsigned)M + m])
; DI void unit(const int wv, const Params& p, int l, int b, int g, int qt, LAS unsigned char* lds) {
;     ...
;         const float lt = lr + __shfl_xor(lr, 32); const float gt = sigmoid_f(ATT_GL(1)) * ((lt > 0.f) ? 1.f / lt : 0.f);
; #pragma unroll
;         for (int dt = 0; dt < 4; ++dt)
; #pragma unroll
;             for (int i = 0; i < 8; ++i) { const unsigned pv = outp[(dt * 8 + i) * 64]; outp[(dt * 8 + i) * 64] = pk2(bflo(pv) + gt * O[dt][2 * i], bfhi(pv) + gt * O[dt][2 * i + 1]); }
;     }
;     {
;         const char* kb = (const char*)(P + (size_t)b * T * PWID + PC_KW + g * 128);
;         const char* vb = (const char*)(Vt + (size_t)(VR_VW + g * 128) * M + (size_t)b * T);
;         const int j0 = (qt >= 8) ? qt - 8 : 0;
;         const unsigned long long wt = ((qt == 63) ? ~0ull : ((1ull << (qt + 1)) - 1ull)) & ~((1ull << j0) - 1ull);
.LBB0_595:
	s_mov_b32 s0, 0x804000
	v_add3_u32 v160, v222, v212, s0
	v_lshl_add_u64 v[64:65], v[160:161], 1, s[82:83]
	s_barrier
	v_mov_b32_e32 v94, v207
	ds_bpermute_b32 v80, v214, v193
	ds_read2st64_b32 v[64:65], v221 offset1:1
	ds_read2st64_b32 v[66:67], v221 offset0:2 offset1:3
	ds_read2st64_b32 v[68:69], v221 offset0:4 offset1:5
	ds_read2st64_b32 v[70:71], v221 offset0:6 offset1:7
	ds_read2st64_b32 v[72:73], v221 offset0:8 offset1:9
	ds_read2st64_b32 v[74:75], v221 offset0:10 offset1:11
	ds_read2st64_b32 v[76:77], v221 offset0:12 offset1:13
	ds_read2st64_b32 v[78:79], v221 offset0:14 offset1:15
	s_waitcnt lgkmcnt(7)
	v_and_b32_e32 v81, 0xffff0000, v64
	s_waitcnt lgkmcnt(3)
	v_lshlrev_b32_e32 v88, 16, v72
	v_and_b32_e32 v89, 0xffff0000, v72
	v_add_f32_e32 v95, v193, v80
	v_div_scale_f32 v96, s[2:3], v95, v95, 1.0
	v_rcp_f32_e32 v97, v96
	s_waitcnt lgkmcnt(1)
	v_lshlrev_b32_e32 v92, 16, v76
	v_and_b32_e32 v93, 0xffff0000, v76
	v_div_scale_f32 v76, vcc, 1.0, v95, 1.0
	v_fma_f32 v98, -v96, v97, 1.0
	v_fmac_f32_e32 v97, v98, v97
	v_mul_f32_e32 v98, v76, v97
	v_fma_f32 v99, -v96, v98, v76
	v_fmac_f32_e32 v98, v99, v97
	v_fma_f32 v76, -v96, v98, v76
	v_div_fmas_f32 v76, v76, v97, v98
	v_div_fixup_f32 v76, v76, v95, 1.0
	v_cmp_lt_f32_e32 vcc, 0, v95
	v_lshlrev_b32_e32 v80, 16, v64
	v_lshlrev_b32_e32 v64, 16, v65
	v_cndmask_b32_e32 v76, 0, v76, vcc
	v_and_b32_e32 v65, 0xffff0000, v65
	v_lshlrev_b32_e32 v72, 16, v73
	v_and_b32_e32 v73, 0xffff0000, v73
	v_lshlrev_b32_e32 v82, 16, v66
	v_and_b32_e32 v83, 0xffff0000, v66
	v_lshlrev_b32_e32 v66, 16, v67
	v_and_b32_e32 v67, 0xffff0000, v67
	v_lshlrev_b32_e32 v84, 16, v68
	v_and_b32_e32 v85, 0xffff0000, v68
	v_lshlrev_b32_e32 v68, 16, v69
	v_and_b32_e32 v69, 0xffff0000, v69
	v_lshlrev_b32_e32 v86, 16, v70
	v_and_b32_e32 v87, 0xffff0000, v70
	v_lshlrev_b32_e32 v70, 16, v71
	v_and_b32_e32 v71, 0xffff0000, v71
	v_lshlrev_b32_e32 v90, 16, v74
	v_and_b32_e32 v91, 0xffff0000, v74
	v_lshlrev_b32_e32 v74, 16, v75
	v_and_b32_e32 v75, 0xffff0000, v75
	v_readlane_b32 s2, v255, 10
	s_sub_i32 s0, 64, s76
	v_readlane_b32 s3, v255, 11
	s_and_b64 s[2:3], s[2:3], exec
	s_cselect_b32 s1, 0x400000, 0
	s_add_u32 s6, s82, s1
	s_addc_u32 s7, s83, 0
	s_lshl_b64 s[0:1], -1, s0
	s_not_b64 s[2:3], s[0:1]
	v_mov_b32_e32 v189, v161
	v_mov_b32_e32 v197, 0
	s_movk_i32 s90, 0x110
	s_waitcnt vmcnt(0)
	v_lshlrev_b32_e32 v94, 16, v94
	v_mul_f32_e32 v94, 0xbfb8aa3b, v94
	v_exp_f32_e32 v94, v94
	s_nop 0
	v_add_f32_e32 v94, 1.0, v94
	v_rcp_f32_e32 v94, v94
	s_nop 0
	v_mul_f32_e32 v76, v76, v94
	v_pk_fma_f32 v[48:49], v[48:49], v[76:77], v[80:81] op_sel_hi:[1,0,1]
	v_pk_fma_f32 v[50:51], v[50:51], v[76:77], v[64:65] op_sel_hi:[1,0,1]
	v_pk_fma_f32 v[32:33], v[32:33], v[76:77], v[88:89] op_sel_hi:[1,0,1]
	v_pk_fma_f32 v[34:35], v[34:35], v[76:77], v[72:73] op_sel_hi:[1,0,1]
	v_pk_fma_f32 v[52:53], v[52:53], v[76:77], v[82:83] op_sel_hi:[1,0,1]
	v_pk_fma_f32 v[54:55], v[54:55], v[76:77], v[66:67] op_sel_hi:[1,0,1]
	v_pk_fma_f32 v[56:57], v[56:57], v[76:77], v[84:85] op_sel_hi:[1,0,1]
	v_pk_fma_f32 v[58:59], v[58:59], v[76:77], v[68:69] op_sel_hi:[1,0,1]
	v_pk_fma_f32 v[60:61], v[60:61], v[76:77], v[86:87] op_sel_hi:[1,0,1]
	v_pk_fma_f32 v[62:63], v[62:63], v[76:77], v[70:71] op_sel_hi:[1,0,1]
	v_pk_fma_f32 v[36:37], v[36:37], v[76:77], v[90:91] op_sel_hi:[1,0,1]
	v_pk_fma_f32 v[38:39], v[38:39], v[76:77], v[74:75] op_sel_hi:[1,0,1]
	v_cvt_pk_bf16_f32 v48, v48, v49
	v_cvt_pk_bf16_f32 v49, v50, v51
	v_cvt_pk_bf16_f32 v32, v32, v33
	v_cvt_pk_bf16_f32 v33, v34, v35
	v_cvt_pk_bf16_f32 v50, v52, v53
	v_cvt_pk_bf16_f32 v51, v54, v55
	v_cvt_pk_bf16_f32 v52, v56, v57
	v_cvt_pk_bf16_f32 v53, v58, v59
	v_cvt_pk_bf16_f32 v54, v60, v61
	v_cvt_pk_bf16_f32 v55, v62, v63
	v_cvt_pk_bf16_f32 v34, v36, v37
	v_cvt_pk_bf16_f32 v35, v38, v39
	ds_write2st64_b32 v221, v48, v49 offset1:1
	ds_write2st64_b32 v221, v50, v51 offset0:2 offset1:3
	ds_write2st64_b32 v221, v52, v53 offset0:4 offset1:5
	ds_write2st64_b32 v221, v54, v55 offset0:6 offset1:7
	ds_write2st64_b32 v221, v32, v33 offset0:8 offset1:9
	ds_write2st64_b32 v221, v34, v35 offset0:10 offset1:11
	v_lshlrev_b32_e32 v32, 16, v77
	v_and_b32_e32 v33, 0xffff0000, v77
	v_pk_fma_f32 v[40:41], v[40:41], v[76:77], v[92:93] op_sel_hi:[1,0,1]
	v_pk_fma_f32 v[32:33], v[42:43], v[76:77], v[32:33] op_sel_hi:[1,0,1]
	v_cvt_pk_bf16_f32 v36, v40, v41
	v_cvt_pk_bf16_f32 v32, v32, v33
	ds_write2st64_b32 v221, v36, v32 offset0:12 offset1:13
	s_waitcnt lgkmcnt(7)
	v_lshlrev_b32_e32 v32, 16, v78
	v_and_b32_e32 v33, 0xffff0000, v78
	v_pk_fma_f32 v[32:33], v[44:45], v[76:77], v[32:33] op_sel_hi:[1,0,1]
	v_mov_b32_e32 v42, v197
	v_cvt_pk_bf16_f32 v34, v32, v33
	v_lshlrev_b32_e32 v32, 16, v79
	v_and_b32_e32 v33, 0xffff0000, v79
	v_pk_fma_f32 v[32:33], v[46:47], v[76:77], v[32:33] op_sel_hi:[1,0,1]
	v_mov_b32_e32 v43, v197
	v_cvt_pk_bf16_f32 v35, v32, v33
	ds_read2st64_b32 v[32:33], v221 offset0:16 offset1:17
	ds_write2st64_b32 v221, v34, v35 offset0:14 offset1:15
	ds_read2st64_b32 v[34:35], v221 offset0:18 offset1:19
	ds_read2st64_b32 v[36:37], v221 offset0:20 offset1:21
	ds_read2st64_b32 v[38:39], v221 offset0:22 offset1:23
	v_mov_b32_e32 v44, v197
	v_mov_b32_e32 v45, v197
	s_waitcnt lgkmcnt(4)
	v_lshlrev_b32_e32 v40, 16, v32
	v_and_b32_e32 v41, 0xffff0000, v32
	v_pk_fma_f32 v[16:17], v[16:17], v[76:77], v[40:41] op_sel_hi:[1,0,1]
	v_mov_b32_e32 v40, v197
	v_cvt_pk_bf16_f32 v32, v16, v17
	v_lshlrev_b32_e32 v16, 16, v33
	v_and_b32_e32 v17, 0xffff0000, v33
	v_pk_fma_f32 v[16:17], v[18:19], v[76:77], v[16:17] op_sel_hi:[1,0,1]
	v_mov_b32_e32 v33, v197
	v_cvt_pk_bf16_f32 v16, v16, v17
	ds_write2st64_b32 v221, v32, v16 offset0:16 offset1:17
	s_waitcnt lgkmcnt(3)
; DI unsigned pk2(float lo, float hi) { f32x2 v = {lo, hi}; bf16x2n b = __builtin_convertvector(v, bf16x2n); return __builtin_bit_cast(unsigned, b); }
; DI void unit(const int wv, const Params& p, int l, int b, int g, int qt, LAS unsigned char* lds) {
;     ...
;             for (int i = 0; i < 8; ++i) { const unsigned pv = outp[(dt * 8 + i) * 64]; outp[(dt * 8 + i) * 64] = pk2(bflo(pv) + gt * O[dt][2 * i], bfhi(pv) + gt * O[dt][2 * i + 1]); }
	v_lshlrev_b32_e32 v16, 16, v34
	v_and_b32_e32 v17, 0xffff0000, v34
	v_pk_fma_f32 v[16:17], v[20:21], v[76:77], v[16:17] op_sel_hi:[1,0,1]
	v_mov_b32_e32 v32, 0
	v_cvt_pk_bf16_f32 v18, v16, v17
	v_lshlrev_b32_e32 v16, 16, v35
	v_and_b32_e32 v17, 0xffff0000, v35
	v_pk_fma_f32 v[16:17], v[22:23], v[76:77], v[16:17] op_sel_hi:[1,0,1]
	v_mov_b32_e32 v34, v197
	v_cvt_pk_bf16_f32 v16, v16, v17
	ds_write2st64_b32 v221, v18, v16 offset0:18 offset1:19
	s_waitcnt lgkmcnt(3)
	v_lshlrev_b32_e32 v16, 16, v36
	v_and_b32_e32 v17, 0xffff0000, v36
	v_pk_fma_f32 v[16:17], v[24:25], v[76:77], v[16:17] op_sel_hi:[1,0,1]
	v_mov_b32_e32 v35, v197
	v_cvt_pk_bf16_f32 v18, v16, v17
	v_lshlrev_b32_e32 v16, 16, v37
	v_and_b32_e32 v17, 0xffff0000, v37
	v_pk_fma_f32 v[16:17], v[26:27], v[76:77], v[16:17] op_sel_hi:[1,0,1]
	v_mov_b32_e32 v26, v197
	v_cvt_pk_bf16_f32 v16, v16, v17
	ds_write2st64_b32 v221, v18, v16 offset0:20 offset1:21
	s_waitcnt lgkmcnt(3)
	v_lshlrev_b32_e32 v16, 16, v38
	v_and_b32_e32 v17, 0xffff0000, v38
	v_pk_fma_f32 v[16:17], v[28:29], v[76:77], v[16:17] op_sel_hi:[1,0,1]
	v_mov_b32_e32 v27, v197
	v_cvt_pk_bf16_f32 v18, v16, v17
	v_lshlrev_b32_e32 v16, 16, v39
	v_and_b32_e32 v17, 0xffff0000, v39
	v_pk_fma_f32 v[16:17], v[30:31], v[76:77], v[16:17] op_sel_hi:[1,0,1]
	v_mov_b32_e32 v28, v197
	v_cvt_pk_bf16_f32 v19, v16, v17
	ds_read2st64_b32 v[16:17], v221 offset0:24 offset1:25
	ds_write2st64_b32 v221, v18, v19 offset0:22 offset1:23
	ds_read2st64_b32 v[18:19], v221 offset0:26 offset1:27
	ds_read2st64_b32 v[20:21], v221 offset0:28 offset1:29
	ds_read2st64_b32 v[22:23], v221 offset0:30 offset1:31
	v_mov_b32_e32 v29, v197
	v_mov_b32_e32 v30, v197
	s_waitcnt lgkmcnt(4)
	v_lshlrev_b32_e32 v24, 16, v16
	v_and_b32_e32 v25, 0xffff0000, v16
	v_pk_fma_f32 v[0:1], v[0:1], v[76:77], v[24:25] op_sel_hi:[1,0,1]
	v_mov_b32_e32 v24, v197
	v_cvt_pk_bf16_f32 v16, v0, v1
	v_lshlrev_b32_e32 v0, 16, v17
	v_and_b32_e32 v1, 0xffff0000, v17
	v_pk_fma_f32 v[0:1], v[2:3], v[76:77], v[0:1] op_sel_hi:[1,0,1]
	v_mov_b32_e32 v17, v197
	v_cvt_pk_bf16_f32 v0, v0, v1
	ds_write2st64_b32 v221, v16, v0 offset0:24 offset1:25
	s_waitcnt lgkmcnt(3)
	v_lshlrev_b32_e32 v0, 16, v18
	v_and_b32_e32 v1, 0xffff0000, v18
	v_pk_fma_f32 v[0:1], v[4:5], v[76:77], v[0:1] op_sel_hi:[1,0,1]
	v_mov_b32_e32 v16, 0
	v_cvt_pk_bf16_f32 v2, v0, v1
	v_lshlrev_b32_e32 v0, 16, v19
	v_and_b32_e32 v1, 0xffff0000, v19
	v_pk_fma_f32 v[0:1], v[6:7], v[76:77], v[0:1] op_sel_hi:[1,0,1]
	v_mov_b32_e32 v18, v197
	v_cvt_pk_bf16_f32 v0, v0, v1
	ds_write2st64_b32 v221, v2, v0 offset0:26 offset1:27
	s_waitcnt lgkmcnt(3)
	v_lshlrev_b32_e32 v0, 16, v20
	v_and_b32_e32 v1, 0xffff0000, v20
	v_pk_fma_f32 v[0:1], v[8:9], v[76:77], v[0:1] op_sel_hi:[1,0,1]
	v_mov_b32_e32 v19, v197
	v_cvt_pk_bf16_f32 v2, v0, v1
	v_lshlrev_b32_e32 v0, 16, v21
	v_and_b32_e32 v1, 0xffff0000, v21
	v_pk_fma_f32 v[0:1], v[10:11], v[76:77], v[0:1] op_sel_hi:[1,0,1]
	v_mov_b32_e32 v11, v197
	v_cvt_pk_bf16_f32 v0, v0, v1
	ds_write2st64_b32 v221, v2, v0 offset0:28 offset1:29
	s_waitcnt lgkmcnt(3)
; #define LAS __attribute__((address_space(3)))
; DI unsigned pk2(float lo, float hi) { f32x2 v = {lo, hi}; bf16x2n b = __builtin_convertvector(v, bf16x2n); return __builtin_bit_cast(unsigned, b); }
; #define ATT_LOAD(j) do { _Pragma("unroll") for (int _i = 0; _i < 2; ++_i) { const int _c = tid + 512 * _i; \
;         kr[_i] = *(const u32x4*)(kbase + (size_t)(64 * (j) + (_c >> 4)) * ldk + (_c & 15) * 16); \
;         if (MODE != 0) vr[_i] = *(const u32x4*)(vbase + (size_t)(_c >> 3) * ldv + (size_t)(j) * 128 + (_c & 7) * 16); } } while (0)
; #define ATT_STORE(LB) do { _Pragma("unroll") for (int _i = 0; _i < 2; ++_i) { const int _c = tid + 512 * _i; \
;         *(LAS u32x4*)((LB) + K_OFF + (_c >> 4) * KST + (_c & 15) * 16) = kr[_i]; \
;         if (MODE != 0) { LAS u32x2* _d = (LAS u32x2*)((LB) + V_OFF + (_c >> 3) * VST + (_c & 7) * 16); _d[0] = (u32x2){vr[_i].x, vr[_i].y}; _d[1] = (u32x2){vr[_i].z, vr[_i].w}; } } } while (0)
; #define ATT_GK(k) wave_max(fmaxf(fabsf(p.k_gain[(l * 3 + (k)) * 128 + lane]), fabsf(p.k_gain[(l * 3 + (k)) * 128 + lane + 64])))
; template <int MODE> ...
;     ...
;     int j = __builtin_ctzll(tiles); tiles &= tiles - 1;
;     LAS unsigned char* const lds0 = lds;
;     ATT_LOAD(j); ATT_STORE(lds0);
;     __syncthreads();
; DI void unit(const int wv, const Params& p, int l, int b, int g, int qt, LAS unsigned char* lds) {
;     ...
;             for (int i = 0; i < 8; ++i) { const unsigned pv = outp[(dt * 8 + i) * 64]; outp[(dt * 8 + i) * 64] = pk2(bflo(pv) + gt * O[dt][2 * i], bfhi(pv) + gt * O[dt][2 * i + 1]); }
;     }
;     {
;         const char* kb = (const char*)(P + (size_t)b * T * PWID + PC_KW + g * 128);
;         const char* vb = (const char*)(Vt + (size_t)(VR_VW + g * 128) * M + (size_t)b * T);
;         const int j0 = (qt >= 8) ? qt - 8 : 0;
;         const unsigned long long wt = ((qt == 63) ? ~0ull : ((1ull << (qt + 1)) - 1ull)) & ~((1ull << j0) - 1ull);
;         float lr = 0.f;
; #pragma unroll
;         for (int dt = 0; dt < 4; ++dt)
; #pragma unroll
;             for (int i = 0; i < 16; ++i) O[dt][i] = 0.f;
;         branch<3>(wv, lds, qf, kb, (long)PWID * 2, vb, (long)M * 2, wt, ~0ull, 0ull, qt, t_tok, sc_l2, sl_l2, qn * ATT_GK(2), 0ull, 0.f, lr, O, nullptr);
	v_lshlrev_b32_e32 v0, 16, v22
	v_and_b32_e32 v1, 0xffff0000, v22
	v_pk_fma_f32 v[0:1], v[12:13], v[76:77], v[0:1] op_sel_hi:[1,0,1]
	v_mov_b32_e32 v12, v197
	v_cvt_pk_bf16_f32 v2, v0, v1
	v_lshlrev_b32_e32 v0, 16, v23
	v_and_b32_e32 v1, 0xffff0000, v23
	v_pk_fma_f32 v[0:1], v[14:15], v[76:77], v[0:1] op_sel_hi:[1,0,1]
	v_mov_b32_e32 v13, v197
	v_cvt_pk_bf16_f32 v0, v0, v1
	ds_write2st64_b32 v221, v2, v0 offset0:30 offset1:31
	global_load_dword v8, v[186:187], off offset:1024
	global_load_dword v9, v[186:187], off offset:1280
	v_sub_u32_e64 v0, s85, 8 clamp
	v_mov_b32_e32 v14, v197
	v_readfirstlane_b32 s0, v0
	s_lshl_b64 s[4:5], -1, s0
	s_lshl_b32 s0, s14, 1
	s_add_u32 s8, s12, s0
	s_addc_u32 s9, s13, 0
	s_lshl_b32 s0, s15, 1
	s_add_u32 s0, s6, s0
	s_addc_u32 s1, s7, 0
	s_add_u32 s0, s0, 0x800000
	s_addc_u32 s1, s1, 0
	s_cmp_lg_u32 s76, 0
	s_cselect_b32 s3, s3, -1
	s_cselect_b32 s2, s2, -1
	s_and_b64 s[2:3], s[2:3], s[4:5]
	s_mov_b32 s4, -1
	s_ff1_i32_b64 s6, s[2:3]
	v_mbcnt_lo_u32_b32 v0, s4, 0
	v_mbcnt_hi_u32_b32 v0, s4, v0
	v_add_u32_e32 v10, s64, v0
	s_add_u32 s4, s2, -1
	v_lshlrev_b32_e32 v2, 4, v10
	v_and_b32_e32 v160, 0xf0, v2
	v_lshl_add_u64 v[0:1], s[8:9], 0, v[160:161]
	s_mov_b64 s[8:9], 0x1600
	s_addc_u32 s5, s3, -1
	s_lshl_b32 s7, s6, 6
	v_lshl_add_u64 v[186:187], v[0:1], 0, s[8:9]
	s_lshl_b32 s8, s6, 7
	v_ashrrev_i32_e32 v4, 3, v10
	s_add_u32 s8, s0, s8
	v_ashrrev_i32_e32 v196, 4, v10
	v_ashrrev_i32_e32 v5, 31, v4
	s_addc_u32 s9, s1, 0
	v_and_b32_e32 v188, 0x70, v2
	v_add_u32_e32 v2, s7, v196
	v_lshlrev_b64 v[190:191], 15, v[4:5]
	v_add_u32_e32 v5, 0x200, v10
	v_lshl_add_u64 v[0:1], s[8:9], 0, v[188:189]
	v_mad_i64_i32 v[2:3], s[8:9], v2, s68, v[186:187]
	v_ashrrev_i32_e32 v198, 4, v5
	v_lshl_add_u64 v[6:7], v[0:1], 0, v[190:191]
	global_load_dwordx4 v[144:147], v[2:3], off
	global_load_dwordx4 v[148:151], v[6:7], off
	v_add_u32_e32 v2, s7, v198
	v_mad_i64_i32 v[2:3], s[8:9], v2, s68, v[186:187]
	global_load_dwordx4 v[152:155], v[2:3], off
	v_ashrrev_i32_e32 v2, 3, v5
	v_ashrrev_i32_e32 v3, 31, v2
	v_lshlrev_b64 v[192:193], 15, v[2:3]
	v_lshl_add_u64 v[0:1], v[0:1], 0, v[192:193]
	global_load_dwordx4 v[156:159], v[0:1], off
	s_movk_i32 s7, 0x110
	s_movk_i32 s8, 0x88
	v_add_u32_e32 v3, 0, v188
	s_mov_b32 s9, 0
	s_and_b64 s[4:5], s[4:5], s[2:3]
	v_lshl_add_u64 v[194:195], s[0:1], 0, v[188:189]
	v_mov_b32_e32 v6, v197
	v_mov_b32_e32 v7, v197
	v_mov_b32_e32 v15, v197
	v_mov_b32_e32 v20, v197
	v_mov_b32_e32 v21, v197
	v_mov_b32_e32 v22, v197
	v_mov_b32_e32 v23, v197
	v_mov_b32_e32 v25, v197
	v_mov_b32_e32 v31, v197
	v_mov_b32_e32 v36, v197
	v_mov_b32_e32 v37, v197
	v_mov_b32_e32 v38, v197
	v_mov_b32_e32 v39, v197
	v_mov_b32_e32 v41, v197
	v_mov_b32_e32 v46, v197
	v_mov_b32_e32 v47, v197
	s_waitcnt vmcnt(5)
	v_max_f32_e64 v1, |v8|, |v8|
	s_waitcnt vmcnt(4)
	v_max_f32_e64 v0, |v9|, |v9|
	v_max_f32_e32 v0, v1, v0
	ds_bpermute_b32 v1, v216, v0
	v_mul_lo_u32 v216, v4, s8
	v_add3_u32 v4, v3, v216, s84
	v_mov_b32_e32 v8, v197
	v_mov_b32_e32 v9, v197
	s_waitcnt lgkmcnt(0)
	v_max_f32_e32 v1, v1, v1
	v_max_f32_e32 v0, v0, v1
	ds_bpermute_b32 v1, v217, v0
	v_mul_lo_u32 v217, v198, s7
	v_mov_b32_e32 v48, 0
	v_mov_b32_e32 v49, v197
	v_mov_b32_e32 v50, v197
	s_waitcnt lgkmcnt(0)
	v_max_f32_e32 v1, v1, v1
	v_max_f32_e32 v0, v0, v1
	ds_bpermute_b32 v1, v218, v0
	v_mul_lo_u32 v218, v2, s8
	s_sub_i32 s8, 55, s76
	v_mov_b32_e32 v2, v197
	v_mov_b32_e32 v51, v197
	s_waitcnt lgkmcnt(0)
	v_max_f32_e32 v1, v1, v1
	v_max_f32_e32 v0, v0, v1
	ds_bpermute_b32 v1, v219, v0
	v_mov_b32_e32 v52, v197
	v_mov_b32_e32 v53, v197
	v_mov_b32_e32 v54, v197
	v_mov_b32_e32 v55, v197
	s_waitcnt lgkmcnt(0)
	v_max_f32_e32 v1, v1, v1
	v_max_f32_e32 v0, v0, v1
	ds_bpermute_b32 v1, v220, v0
	v_mov_b32_e32 v56, v197
	v_mov_b32_e32 v57, v197
	v_mov_b32_e32 v58, v197
	v_mov_b32_e32 v59, v197
	s_waitcnt lgkmcnt(0)
	v_max_f32_e32 v1, v1, v1
	v_max_f32_e32 v0, v0, v1
	ds_bpermute_b32 v1, v214, v0
	v_mov_b32_e32 v60, v197
	v_mov_b32_e32 v61, v197
	v_mov_b32_e32 v62, v197
	v_mov_b32_e32 v63, v197
	s_waitcnt lgkmcnt(0)
	v_max_f32_e32 v1, v1, v1
	v_max_f32_e32 v0, v0, v1
	v_mul_f32_e32 v199, v215, v0
	v_add_u32_e32 v1, 0, v160
	v_mul_lo_u32 v215, v196, s7
	v_add_u32_e32 v5, v1, v215
	v_add_u32_e32 v1, v1, v217
	s_waitcnt vmcnt(3)
	ds_write_b128 v5, v[144:147]
	s_waitcnt vmcnt(2)
	ds_write2_b64 v4, v[148:149], v[150:151] offset1:1
	s_waitcnt vmcnt(1)
	ds_write_b128 v1, v[152:155]
	v_add3_u32 v1, v3, v218, s84
	v_bfe_u32 v0, v10, 5, 1
	v_lshlrev_b32_e32 v220, 4, v0
	v_lshlrev_b32_e32 v223, 3, v0
	s_waitcnt vmcnt(0)
	ds_write2_b64 v1, v[156:157], v[158:159] offset1:1
	v_and_b32_e32 v1, 31, v10
	v_mul_u32_u24_e32 v219, 0x110, v1
	v_mul_u32_u24_e32 v189, 0x88, v1
	v_lshlrev_b32_e32 v224, 2, v0
	v_mov_b32_e32 v0, 0
	v_mov_b32_e32 v1, v197
	v_mov_b32_e32 v3, v197
	v_mov_b32_e32 v4, v197
	v_mov_b32_e32 v5, v197
	v_mov_b32_e32 v10, v197
	s_waitcnt lgkmcnt(0)
	s_barrier
	s_branch .LBB0_598

; #define LAS __attribute__((address_space(3)))
; __global__ void __launch_bounds__(512, 2) mega(Params p) {
;     extern __shared__ __attribute__((aligned(16))) unsigned char lds_raw[];
;     LAS unsigned char* lds = (LAS unsigned char*)lds_raw;
;     cg::grid_group grid = cg::this_grid();
;     const int wv = __builtin_amdgcn_readfirstlane((int)threadIdx.x >> 6);
	.amdhsa_kernel _Z4mega6Params
		.amdhsa_group_segment_fixed_size 0
		.amdhsa_private_segment_fixed_size 0
		.amdhsa_kernarg_size 408
		.amdhsa_user_sgpr_count 2
		.amdhsa_user_sgpr_dispatch_ptr 0
		.amdhsa_user_sgpr_queue_ptr 0
		.amdhsa_user_sgpr_kernarg_segment_ptr 1
		.amdhsa_user_sgpr_dispatch_id 0
		.amdhsa_user_sgpr_kernarg_preload_length 0
		.amdhsa_user_sgpr_kernarg_preload_offset 0
		.amdhsa_user_sgpr_private_segment_size 0
		.amdhsa_uses_dynamic_stack 0
		.amdhsa_enable_private_segment 0
		.amdhsa_system_sgpr_workgroup_id_x 1
		.amdhsa_system_sgpr_workgroup_id_y 0
		.amdhsa_system_sgpr_workgroup_id_z 0
		.amdhsa_system_sgpr_workgroup_info 0
		.amdhsa_system_vgpr_workitem_id 2
		.amdhsa_next_free_vgpr 256
		.amdhsa_next_free_sgpr 100
		.amdhsa_accum_offset 256
		.amdhsa_reserve_vcc 1
		.amdhsa_float_round_mode_32 0
		.amdhsa_float_round_mode_16_64 0
		.amdhsa_float_denorm_mode_32 3
		.amdhsa_float_denorm_mode_16_64 3
		.amdhsa_dx10_clamp 1
		.amdhsa_ieee_mode 1
		.amdhsa_fp16_overflow 0
		.amdhsa_tg_split 0
		.amdhsa_exception_fp_ieee_invalid_op 0
		.amdhsa_exception_fp_denorm_src 0
		.amdhsa_exception_fp_ieee_div_zero 0
		.amdhsa_exception_fp_ieee_overflow 0
		.amdhsa_exception_fp_ieee_underflow 0
		.amdhsa_exception_fp_ieee_inexact 0
		.amdhsa_exception_int_div_zero 0
	.end_amdhsa_kernel
